# hgrn_scan: dd/em via 2 wide loads + ds_bpermute (was 32 loads), next-group state prefetch
# speedup vs baseline: 1.0397x; 1.0100x over previous
.LBB0_491:
	v_lshlrev_b32_e32 v0, 2, v37
	v_and_b32_e32 v10, 24, v0
	v_lshrrev_b32_e32 v0, 3, v37
	v_and_b32_e32 v11, 0x1e0, v0
	v_ashrrev_i32_e32 v8, 13, v36
	v_lshlrev_b32_e32 v0, 1, v36
	v_lshrrev_b32_e32 v2, 4, v36
	v_and_b32_e32 v0, 6, v0
	v_ashrrev_i32_e32 v9, 31, v8
	v_lshlrev_b32_e32 v12, 1, v37
	v_and_or_b32 v0, v2, s9, v0
	v_lshlrev_b64 v[2:3], 7, v[8:9]
	v_lshlrev_b64 v[6:7], 16, v[8:9]
	v_lshlrev_b64 v[8:9], 22, v[8:9]
	v_lshlrev_b32_e32 v0, 2, v0
	v_or3_b32 v6, v11, v10, v6
	v_and_or_b32 v8, v12, s10, v8
	v_lshl_add_u64 v[4:5], s[6:7], 0, v[0:1]
	v_lshl_add_u64 v[6:7], s[12:13], 0, v[6:7]
	v_lshl_add_u64 v[8:9], s[14:15], 0, v[8:9]
	s_mov_b64 s[60:61], 0
	v_mov_b32_e32 v16, 0
	v_mov_b32_e32 v17, v1
	v_mbcnt_lo_u32_b32 v162, -1, 0
	v_mbcnt_hi_u32_b32 v162, -1, v162
	v_lshrrev_b32_e32 v150, 2, v162
	v_mov_b32_e32 v151, 0
	v_and_b32_e32 v156, 3, v162
	v_lshlrev_b32_e32 v156, 2, v156
	v_add_u32_e32 v154, -15, v150
	v_lshlrev_b32_e32 v154, 9, v154
	v_ashrrev_i32_e32 v155, 31, v154
	s_mov_b32 s100, 0xfff88000
	s_mov_b32 s101, -1
	s_mov_b64 s[98:99], 0x8000
	v_lshl_add_u64 v[148:149], v[8:9], 0, s[100:101]
	global_load_dword v132, v[148:149], off
	v_lshl_add_u64 v[148:149], v[148:149], 0, s[98:99]
	global_load_dword v133, v[148:149], off
	v_lshl_add_u64 v[148:149], v[148:149], 0, s[98:99]
	global_load_dword v134, v[148:149], off
	v_lshl_add_u64 v[148:149], v[148:149], 0, s[98:99]
	global_load_dword v135, v[148:149], off
	v_lshl_add_u64 v[148:149], v[148:149], 0, s[98:99]
	global_load_dword v136, v[148:149], off
	v_lshl_add_u64 v[148:149], v[148:149], 0, s[98:99]
	global_load_dword v137, v[148:149], off
	v_lshl_add_u64 v[148:149], v[148:149], 0, s[98:99]
	global_load_dword v138, v[148:149], off
	v_lshl_add_u64 v[148:149], v[148:149], 0, s[98:99]
	global_load_dword v139, v[148:149], off
	v_lshl_add_u64 v[148:149], v[148:149], 0, s[98:99]
	global_load_dword v140, v[148:149], off
	v_lshl_add_u64 v[148:149], v[148:149], 0, s[98:99]
	global_load_dword v141, v[148:149], off
	v_lshl_add_u64 v[148:149], v[148:149], 0, s[98:99]
	global_load_dword v142, v[148:149], off
	v_lshl_add_u64 v[148:149], v[148:149], 0, s[98:99]
	global_load_dword v143, v[148:149], off
	v_lshl_add_u64 v[148:149], v[148:149], 0, s[98:99]
	global_load_dword v144, v[148:149], off
	v_lshl_add_u64 v[148:149], v[148:149], 0, s[98:99]
	global_load_dword v145, v[148:149], off
	v_lshl_add_u64 v[148:149], v[148:149], 0, s[98:99]
	global_load_dword v146, v[148:149], off
	v_lshl_add_u64 v[148:149], v[148:149], 0, s[98:99]
	global_load_dword v147, v[148:149], off
	v_lshl_add_u64 v[162:163], v[2:3], 0, s[60:61]
	v_add_u32_e32 v162, v162, v150
	v_add_u32_e32 v162, 1, v162
	v_min_u32_e32 v162, 0x7ff, v162
	v_lshlrev_b32_e32 v162, 9, v162
	v_mov_b32_e32 v163, 0
	v_lshl_add_u64 v[148:149], v[4:5], 0, v[162:163]
	global_load_dwordx2 v[160:161], v[148:149], off
	v_lshl_add_u64 v[148:149], v[6:7], 0, v[154:155]
	global_load_dwordx2 v[158:159], v[148:149], off
	s_waitcnt vmcnt(0)
.LBB0_492:
	s_waitcnt vmcnt(16)
	v_lshl_add_u64 v[26:27], v[2:3], 0, s[60:61]
	v_mov_b32_e32 v168, v26
	v_lshl_add_u64 v[12:13], v[26:27], 0, 1
	v_cmp_gt_u64_e64 s[2:3], s[54:55], v[26:27]
	v_add_co_u32_e32 v10, vcc, s11, v8
	s_nop 0
	v_cndmask_b32_e64 v15, v27, v13, s[2:3]
	v_cndmask_b32_e64 v14, v26, v12, s[2:3]
	v_lshlrev_b64 v[14:15], 9, v[14:15]
	v_lshl_add_u64 v[14:15], v[4:5], 0, v[14:15]
	v_lshl_add_u64 v[14:15], v[26:27], 0, 2
	v_cndmask_b32_e64 v19, v13, v15, s[2:3]
	v_cndmask_b32_e64 v18, v12, v14, s[2:3]
	v_lshlrev_b64 v[18:19], 9, v[18:19]
	v_addc_co_u32_e32 v11, vcc, -1, v9, vcc
	v_lshl_add_u64 v[18:19], v[4:5], 0, v[18:19]
	v_add_co_u32_e32 v30, vcc, s16, v6
	v_lshl_add_u64 v[18:19], v[26:27], 0, 3
	v_addc_co_u32_e32 v31, vcc, -1, v7, vcc
	v_cndmask_b32_e64 v21, v15, v19, s[2:3]
	v_cndmask_b32_e64 v20, v14, v18, s[2:3]
	v_add_co_u32_e32 v12, vcc, s17, v8
	v_lshlrev_b64 v[20:21], 9, v[20:21]
	s_nop 0
	v_addc_co_u32_e32 v13, vcc, -1, v9, vcc
	v_lshl_add_u64 v[20:21], v[4:5], 0, v[20:21]
	v_add_co_u32_e32 v14, vcc, s18, v8
	v_lshl_add_u64 v[20:21], v[26:27], 0, 4
	v_addc_co_u32_e32 v15, vcc, -1, v9, vcc
	v_cndmask_b32_e64 v23, v19, v21, s[2:3]
	v_cndmask_b32_e64 v22, v18, v20, s[2:3]
	v_add_co_u32_e32 v18, vcc, s19, v8
	v_lshlrev_b64 v[22:23], 9, v[22:23]
	s_nop 0
	v_addc_co_u32_e32 v19, vcc, -1, v9, vcc
	v_lshl_add_u64 v[22:23], v[4:5], 0, v[22:23]
	v_mov_b32_e32 v0, v132
	v_mov_b32_e32 v111, v133
	v_mov_b32_e32 v113, v134
	v_mov_b32_e32 v115, v135
	v_lshl_add_u64 v[22:23], v[26:27], 0, 5
	v_cndmask_b32_e64 v25, v21, v23, s[2:3]
	v_cndmask_b32_e64 v24, v20, v22, s[2:3]
	v_lshlrev_b64 v[24:25], 9, v[24:25]
	v_lshl_add_u64 v[24:25], v[4:5], 0, v[24:25]
	v_lshl_add_u64 v[24:25], v[26:27], 0, 6
	v_add_co_u32_e32 v20, vcc, s20, v8
	v_cndmask_b32_e64 v35, v23, v25, s[2:3]
	v_cndmask_b32_e64 v34, v22, v24, s[2:3]
	v_addc_co_u32_e32 v21, vcc, -1, v9, vcc
	v_lshlrev_b64 v[34:35], 9, v[34:35]
	v_add_co_u32_e32 v22, vcc, s21, v8
	v_lshl_add_u64 v[34:35], v[4:5], 0, v[34:35]
	s_nop 0
	v_addc_co_u32_e32 v23, vcc, -1, v9, vcc
	v_lshl_add_u64 v[34:35], v[26:27], 0, 7
	v_cndmask_b32_e64 v54, v24, v34, s[2:3]
	v_add_co_u32_e32 v24, vcc, s22, v8
	v_lshl_add_u64 v[62:63], v[26:27], 0, 8
	v_lshl_add_u64 v[66:67], v[26:27], 0, 9
	v_lshl_add_u64 v[68:69], v[26:27], 0, 10
	v_cndmask_b32_e64 v55, v25, v35, s[2:3]
	v_addc_co_u32_e32 v25, vcc, -1, v9, vcc
	v_cndmask_b32_e64 v35, v35, v63, s[2:3]
	v_cndmask_b32_e64 v34, v34, v62, s[2:3]
	v_cndmask_b32_e64 v63, v63, v67, s[2:3]
	v_cndmask_b32_e64 v62, v62, v66, s[2:3]
	v_cndmask_b32_e64 v67, v67, v69, s[2:3]
	v_cndmask_b32_e64 v66, v66, v68, s[2:3]
	v_mov_b32_e32 v117, v136
	v_mov_b32_e32 v118, v137
	v_mov_b32_e32 v119, v138
	v_lshlrev_b64 v[30:31], 9, v[54:55]
	v_lshlrev_b64 v[34:35], 9, v[34:35]
	v_lshlrev_b64 v[62:63], 9, v[62:63]
	v_lshlrev_b64 v[66:67], 9, v[66:67]
	v_lshl_add_u64 v[30:31], v[4:5], 0, v[30:31]
	v_lshl_add_u64 v[34:35], v[4:5], 0, v[34:35]
	v_lshl_add_u64 v[62:63], v[4:5], 0, v[62:63]
	v_lshl_add_u64 v[66:67], v[4:5], 0, v[66:67]
	v_lshl_add_u64 v[72:73], v[26:27], 0, 11
	v_cndmask_b32_e64 v69, v69, v73, s[2:3]
	v_add_co_u32_e32 v30, vcc, s23, v8
	v_cndmask_b32_e64 v68, v68, v72, s[2:3]
	s_nop 0
	v_addc_co_u32_e32 v31, vcc, -1, v9, vcc
	v_add_co_u32_e32 v34, vcc, s24, v8
	v_mov_b32_e32 v120, v139
	s_nop 0
	v_addc_co_u32_e32 v35, vcc, -1, v9, vcc
	v_add_co_u32_e32 v70, vcc, s25, v8
	v_mov_b32_e32 v121, v140
	s_nop 0
	v_addc_co_u32_e32 v71, vcc, -1, v9, vcc
	v_add_co_u32_e32 v74, vcc, s26, v8
	v_mov_b32_e32 v122, v141
	s_nop 0
	v_addc_co_u32_e32 v75, vcc, -1, v9, vcc
	v_add_co_u32_e32 v86, vcc, s27, v8
	v_lshl_add_u64 v[84:85], v[26:27], 0, 12
	s_nop 0
	v_addc_co_u32_e32 v87, vcc, -1, v9, vcc
	v_add_co_u32_e32 v90, vcc, s28, v8
	v_mov_b32_e32 v123, v142
	v_addc_co_u32_e32 v91, vcc, -1, v9, vcc
	v_add_co_u32_e32 v94, vcc, s29, v8
	v_lshlrev_b64 v[68:69], 9, v[68:69]
	v_cndmask_b32_e64 v73, v73, v85, s[2:3]
	v_cndmask_b32_e64 v72, v72, v84, s[2:3]
	v_lshl_add_u64 v[88:89], v[26:27], 0, 13
	v_addc_co_u32_e32 v95, vcc, -1, v9, vcc
	v_lshl_add_u64 v[68:69], v[4:5], 0, v[68:69]
	v_mov_b32_e32 v124, v143
	v_mov_b32_e32 v125, v144
	v_mov_b32_e32 v126, v145
	v_lshlrev_b64 v[72:73], 9, v[72:73]
	v_cndmask_b32_e64 v85, v85, v89, s[2:3]
	v_cndmask_b32_e64 v84, v84, v88, s[2:3]
	v_lshl_add_u64 v[92:93], v[26:27], 0, 14
	v_add_co_u32_e32 v96, vcc, s30, v8
	v_lshl_add_u64 v[72:73], v[4:5], 0, v[72:73]
	v_lshlrev_b64 v[84:85], 9, v[84:85]
	v_cndmask_b32_e64 v89, v89, v93, s[2:3]
	v_cndmask_b32_e64 v88, v88, v92, s[2:3]
	v_addc_co_u32_e32 v97, vcc, -1, v9, vcc
	v_lshl_add_u64 v[98:99], v[26:27], 0, 15
	v_lshl_add_u64 v[26:27], v[26:27], 0, 16
	v_lshl_add_u64 v[84:85], v[4:5], 0, v[84:85]
	v_lshlrev_b64 v[88:89], 9, v[88:89]
	v_cndmask_b32_e64 v93, v93, v99, s[2:3]
	v_cndmask_b32_e64 v92, v92, v98, s[2:3]
	v_cmp_gt_u64_e32 vcc, s[54:55], v[26:27]
	v_lshl_add_u64 v[88:89], v[4:5], 0, v[88:89]
	v_lshlrev_b64 v[92:93], 9, v[92:93]
	v_cndmask_b32_e32 v27, v99, v27, vcc
	v_cndmask_b32_e32 v26, v98, v26, vcc
	v_mov_b32_e32 v127, v146
	s_nop 0
	s_nop 0
	v_mov_b32_e32 v128, v147
	v_lshl_add_u64 v[92:93], v[4:5], 0, v[92:93]
	v_lshlrev_b64 v[26:27], 9, v[26:27]
	v_lshl_add_u64 v[26:27], v[4:5], 0, v[26:27]
	v_lshlrev_b32_e32 v108, 16, v0
	v_add_u32_e32 v162, v168, v150
	v_add_u32_e32 v162, 17, v162
	v_min_u32_e32 v162, 0x7ff, v162
	v_lshlrev_b32_e32 v162, 9, v162
	v_mov_b32_e32 v163, 0
	v_lshl_add_u64 v[164:165], v[4:5], 0, v[162:163]
	v_lshl_add_u64 v[166:167], v[6:7], 0, v[154:155]
	v_lshl_add_u64 v[166:167], v[166:167], 0, s[56:57]
	ds_bpermute_b32 v40, v156, v158 offset:0
	ds_bpermute_b32 v41, v156, v159 offset:0
	ds_bpermute_b32 v28, v156, v160 offset:0
	ds_bpermute_b32 v29, v156, v161 offset:0
	ds_bpermute_b32 v42, v156, v158 offset:16
	ds_bpermute_b32 v43, v156, v159 offset:16
	ds_bpermute_b32 v32, v156, v160 offset:16
	ds_bpermute_b32 v33, v156, v161 offset:16
	ds_bpermute_b32 v44, v156, v158 offset:32
	ds_bpermute_b32 v45, v156, v159 offset:32
	ds_bpermute_b32 v38, v156, v160 offset:32
	ds_bpermute_b32 v39, v156, v161 offset:32
	ds_bpermute_b32 v46, v156, v158 offset:48
	ds_bpermute_b32 v47, v156, v159 offset:48
	ds_bpermute_b32 v48, v156, v160 offset:48
	ds_bpermute_b32 v49, v156, v161 offset:48
	ds_bpermute_b32 v56, v156, v158 offset:64
	ds_bpermute_b32 v57, v156, v159 offset:64
	ds_bpermute_b32 v50, v156, v160 offset:64
	ds_bpermute_b32 v51, v156, v161 offset:64
	ds_bpermute_b32 v58, v156, v158 offset:80
	ds_bpermute_b32 v59, v156, v159 offset:80
	ds_bpermute_b32 v52, v156, v160 offset:80
	ds_bpermute_b32 v53, v156, v161 offset:80
	ds_bpermute_b32 v60, v156, v158 offset:96
	ds_bpermute_b32 v61, v156, v159 offset:96
	ds_bpermute_b32 v54, v156, v160 offset:96
	ds_bpermute_b32 v55, v156, v161 offset:96
	ds_bpermute_b32 v76, v156, v158 offset:112
	ds_bpermute_b32 v77, v156, v159 offset:112
	ds_bpermute_b32 v64, v156, v160 offset:112
	ds_bpermute_b32 v65, v156, v161 offset:112
	ds_bpermute_b32 v78, v156, v158 offset:128
	ds_bpermute_b32 v79, v156, v159 offset:128
	ds_bpermute_b32 v62, v156, v160 offset:128
	ds_bpermute_b32 v63, v156, v161 offset:128
	ds_bpermute_b32 v80, v156, v158 offset:144
	ds_bpermute_b32 v81, v156, v159 offset:144
	ds_bpermute_b32 v66, v156, v160 offset:144
	ds_bpermute_b32 v67, v156, v161 offset:144
	ds_bpermute_b32 v82, v156, v158 offset:160
	ds_bpermute_b32 v83, v156, v159 offset:160
	ds_bpermute_b32 v68, v156, v160 offset:160
	ds_bpermute_b32 v69, v156, v161 offset:160
	ds_bpermute_b32 v100, v156, v158 offset:176
	ds_bpermute_b32 v101, v156, v159 offset:176
	ds_bpermute_b32 v72, v156, v160 offset:176
	ds_bpermute_b32 v73, v156, v161 offset:176
	ds_bpermute_b32 v102, v156, v158 offset:192
	ds_bpermute_b32 v103, v156, v159 offset:192
	ds_bpermute_b32 v84, v156, v160 offset:192
	ds_bpermute_b32 v85, v156, v161 offset:192
	ds_bpermute_b32 v104, v156, v158 offset:208
	ds_bpermute_b32 v105, v156, v159 offset:208
	ds_bpermute_b32 v88, v156, v160 offset:208
	ds_bpermute_b32 v89, v156, v161 offset:208
	ds_bpermute_b32 v106, v156, v158 offset:224
	ds_bpermute_b32 v107, v156, v159 offset:224
	ds_bpermute_b32 v92, v156, v160 offset:224
	ds_bpermute_b32 v93, v156, v161 offset:224
	ds_bpermute_b32 v98, v156, v158 offset:240
	ds_bpermute_b32 v99, v156, v159 offset:240
	ds_bpermute_b32 v26, v156, v160 offset:240
	ds_bpermute_b32 v27, v156, v161 offset:240
	global_load_dwordx2 v[160:161], v[164:165], off
	global_load_dwordx2 v[158:159], v[166:167], off
	v_lshl_add_u64 v[148:149], v[10:11], 0, s[58:59]
	global_load_dword v132, v[148:149], off
	v_lshl_add_u64 v[148:149], v[12:13], 0, s[58:59]
	global_load_dword v133, v[148:149], off
	v_lshl_add_u64 v[148:149], v[14:15], 0, s[58:59]
	global_load_dword v134, v[148:149], off
	v_lshl_add_u64 v[148:149], v[18:19], 0, s[58:59]
	global_load_dword v135, v[148:149], off
	v_lshl_add_u64 v[148:149], v[20:21], 0, s[58:59]
	global_load_dword v136, v[148:149], off
	v_lshl_add_u64 v[148:149], v[22:23], 0, s[58:59]
	global_load_dword v137, v[148:149], off
	v_lshl_add_u64 v[148:149], v[24:25], 0, s[58:59]
	global_load_dword v138, v[148:149], off
	v_lshl_add_u64 v[148:149], v[30:31], 0, s[58:59]
	global_load_dword v139, v[148:149], off
	v_lshl_add_u64 v[148:149], v[34:35], 0, s[58:59]
	global_load_dword v140, v[148:149], off
	v_lshl_add_u64 v[148:149], v[70:71], 0, s[58:59]
	global_load_dword v141, v[148:149], off
	v_lshl_add_u64 v[148:149], v[74:75], 0, s[58:59]
	global_load_dword v142, v[148:149], off
	v_lshl_add_u64 v[148:149], v[86:87], 0, s[58:59]
	global_load_dword v143, v[148:149], off
	v_lshl_add_u64 v[148:149], v[90:91], 0, s[58:59]
	global_load_dword v144, v[148:149], off
	v_lshl_add_u64 v[148:149], v[94:95], 0, s[58:59]
	global_load_dword v145, v[148:149], off
	v_lshl_add_u64 v[148:149], v[96:97], 0, s[58:59]
	global_load_dword v146, v[148:149], off
	v_lshl_add_u64 v[148:149], v[8:9], 0, s[58:59]
	global_load_dword v147, v[148:149], off
	s_waitcnt lgkmcnt(0)
	v_and_b32_e32 v109, 0xffff0000, v0
	v_lshlrev_b32_e32 v110, 16, v111
	v_and_b32_e32 v111, 0xffff0000, v111
	v_pk_fma_f32 v[16:17], v[16:17], v[40:41], v[108:109]
	v_lshlrev_b32_e32 v112, 16, v113
	v_and_b32_e32 v113, 0xffff0000, v113
	v_pk_mul_f32 v[28:29], v[28:29], v[16:17]
	v_pk_fma_f32 v[16:17], v[16:17], v[42:43], v[110:111]
	v_lshlrev_b32_e32 v114, 16, v115
	v_and_b32_e32 v115, 0xffff0000, v115
	v_cvt_pk_bf16_f32 v0, v28, v29
	v_pk_mul_f32 v[28:29], v[32:33], v[16:17]
	v_pk_fma_f32 v[16:17], v[16:17], v[44:45], v[112:113]
	v_lshlrev_b32_e32 v116, 16, v117
	v_and_b32_e32 v117, 0xffff0000, v117
	v_cvt_pk_bf16_f32 v108, v28, v29
	v_pk_mul_f32 v[28:29], v[38:39], v[16:17]
	v_pk_fma_f32 v[16:17], v[16:17], v[46:47], v[114:115]
	v_cvt_pk_bf16_f32 v109, v28, v29
	v_pk_mul_f32 v[28:29], v[48:49], v[16:17]
	v_pk_fma_f32 v[16:17], v[16:17], v[56:57], v[116:117]
	v_cvt_pk_bf16_f32 v46, v28, v29
	v_pk_mul_f32 v[28:29], v[50:51], v[16:17]
	v_lshlrev_b32_e32 v32, 16, v119
	v_cvt_pk_bf16_f32 v47, v28, v29
	v_lshlrev_b32_e32 v28, 16, v118
	v_and_b32_e32 v29, 0xffff0000, v118
	v_and_b32_e32 v33, 0xffff0000, v119
	v_pk_fma_f32 v[16:17], v[16:17], v[58:59], v[28:29]
	v_lshlrev_b32_e32 v38, 16, v120
	v_and_b32_e32 v39, 0xffff0000, v120
	v_pk_mul_f32 v[28:29], v[52:53], v[16:17]
	v_pk_fma_f32 v[16:17], v[16:17], v[60:61], v[32:33]
	v_lshlrev_b32_e32 v40, 16, v121
	v_and_b32_e32 v41, 0xffff0000, v121
	v_cvt_pk_bf16_f32 v48, v28, v29
	v_pk_mul_f32 v[28:29], v[54:55], v[16:17]
	v_pk_fma_f32 v[16:17], v[16:17], v[76:77], v[38:39]
	v_lshlrev_b32_e32 v42, 16, v122
	v_and_b32_e32 v43, 0xffff0000, v122
	v_cvt_pk_bf16_f32 v49, v28, v29
	v_pk_mul_f32 v[28:29], v[64:65], v[16:17]
	v_pk_fma_f32 v[16:17], v[16:17], v[78:79], v[40:41]
	v_cvt_pk_bf16_f32 v50, v28, v29
	v_pk_mul_f32 v[28:29], v[62:63], v[16:17]
	v_pk_fma_f32 v[16:17], v[16:17], v[80:81], v[42:43]
	v_lshlrev_b32_e32 v44, 16, v123
	v_cvt_pk_bf16_f32 v51, v28, v29
	v_pk_mul_f32 v[28:29], v[66:67], v[16:17]
	v_and_b32_e32 v45, 0xffff0000, v123
	v_cvt_pk_bf16_f32 v52, v28, v29
	v_lshlrev_b32_e32 v28, 16, v124
	v_and_b32_e32 v29, 0xffff0000, v124
	v_pk_fma_f32 v[16:17], v[16:17], v[82:83], v[44:45]
	v_lshlrev_b32_e32 v32, 16, v125
	v_and_b32_e32 v33, 0xffff0000, v125
	v_pk_mul_f32 v[44:45], v[68:69], v[16:17]
	v_lshlrev_b32_e32 v38, 16, v126
	v_and_b32_e32 v39, 0xffff0000, v126
	v_cvt_pk_bf16_f32 v44, v44, v45
	s_add_u32 s60, s60, 16
	s_addc_u32 s61, s61, 0
	s_add_i32 s2, s60, -16
	v_lshl_add_u64 v[6:7], v[6:7], 0, s[56:57]
	s_cmpk_gt_u32 s2, 0x6f
	v_pk_fma_f32 v[16:17], v[16:17], v[100:101], v[28:29]
	s_nop 0
	v_pk_mul_f32 v[28:29], v[72:73], v[16:17]
	v_pk_fma_f32 v[16:17], v[16:17], v[102:103], v[32:33]
	v_lshlrev_b32_e32 v40, 16, v127
	v_and_b32_e32 v41, 0xffff0000, v127
	v_cvt_pk_bf16_f32 v45, v28, v29
	v_pk_mul_f32 v[28:29], v[84:85], v[16:17]
	v_pk_fma_f32 v[16:17], v[16:17], v[104:105], v[38:39]
	v_lshlrev_b32_e32 v42, 16, v128
	v_and_b32_e32 v43, 0xffff0000, v128
	v_cvt_pk_bf16_f32 v32, v28, v29
	v_pk_mul_f32 v[28:29], v[88:89], v[16:17]
	v_pk_fma_f32 v[16:17], v[16:17], v[106:107], v[40:41]
	v_cvt_pk_bf16_f32 v33, v28, v29
	v_pk_mul_f32 v[28:29], v[92:93], v[16:17]
	v_pk_fma_f32 v[16:17], v[16:17], v[98:99], v[42:43]
	v_cvt_pk_bf16_f32 v28, v28, v29
	v_pk_mul_f32 v[26:27], v[26:27], v[16:17]
	s_nop 0
	v_cvt_pk_bf16_f32 v26, v26, v27
	global_store_dword v[10:11], v0, off
	global_store_dword v[12:13], v108, off
	global_store_dword v[14:15], v109, off
	global_store_dword v[18:19], v46, off
	global_store_dword v[20:21], v47, off
	global_store_dword v[22:23], v48, off
	global_store_dword v[24:25], v49, off
	global_store_dword v[30:31], v50, off
	global_store_dword v[34:35], v51, off
	global_store_dword v[70:71], v52, off
	global_store_dword v[74:75], v44, off
	global_store_dword v[86:87], v45, off
	global_store_dword v[90:91], v32, off
	global_store_dword v[94:95], v33, off
	global_store_dword v[96:97], v28, off
	global_store_dword v[8:9], v26, off
	v_lshl_add_u64 v[8:9], v[8:9], 0, s[58:59]
	s_cbranch_scc0 .LBB0_492
	v_add_u32_e32 v36, s52, v36
	v_cmp_lt_i32_e32 vcc, s31, v36
	s_or_b64 s[34:35], vcc, s[34:35]
	v_add_u32_e32 v37, s8, v37
	s_andn2_b64 exec, exec, s[34:35]
	s_cbranch_execnz .LBB0_491
